# counter seam after P0 replaces cg grid sync; XCD-local barriers at later seams when census shows one bx%8 group per XCC
# speedup vs baseline: 1.0270x; 1.0270x over previous
.LBB0_2:
	s_load_dword s2, s[0:1], 0xc8
	v_cmp_eq_u32_e64 s[92:93], 0, v196
	s_waitcnt lgkmcnt(0)
	v_writelane_b32 v249, s2, 8
	s_and_saveexec_b64 s[2:3], s[92:93]
	s_cbranch_execz .LBB0_4
	s_add_i32 s5, 0, 0x20080
	v_mov_b32_e32 v1, 0
	v_mov_b32_e32 v2, s5
	s_add_i32 s5, 0, 0x20084
	ds_write_b32 v2, v1
	v_mov_b32_e32 v2, s5
	ds_write_b32 v2, v1
	ds_write_b32 v2, v1 offset:4

.LBB0_12:
	s_or_b64 exec, exec, s[4:5]
	s_cmpk_lg_i32 s82, 0x100
	s_cbranch_scc1 .LBB0_13
	s_waitcnt vmcnt(0)
	s_barrier
	s_and_saveexec_b64 s[0:1], s[92:93]
	s_cbranch_execz .Lsdz_end
	buffer_wbl2 sc1
	s_waitcnt vmcnt(0)
	s_add_u32 s2, s88, 0x8000
	s_addc_u32 s3, s89, 0
	v_mov_b32_e32 v1, 0
	v_mov_b32_e32 v2, 0x5ada1e55
	global_atomic_swap v1, v2, s[2:3]
	s_waitcnt vmcnt(0)
.Lsdz_end:
	s_or_b64 exec, exec, s[0:1]
.LBB0_13:
	s_cmpk_gt_i32 s94, 0x5f
	s_cbranch_scc1 .LBB0_20
	v_lshlrev_b32_e32 v2, 2, v199
	v_add_u32_e32 v11, 0, v2
	v_and_b32_e32 v7, 0x3c0, v196
	v_add_u32_e32 v9, 0x200, v196
	v_lshl_add_u32 v54, v7, 2, v11
	v_and_b32_e32 v7, 0x7c0, v9
	v_lshl_add_u32 v55, v7, 2, v11
	v_lshrrev_b32_e32 v7, 6, v9
	s_movk_i32 s0, 0x7c0
	v_mul_u32_u24_e32 v12, 0x1800, v7
	v_or_b32_e32 v7, 0x400, v196
	v_mov_b32_e32 v14, 0x400
	v_bitop3_b32 v14, v196, s0, v14 bitop3:0xc8
	v_lshrrev_b32_e32 v7, 6, v7
	v_add_u32_e32 v15, 0x600, v196
	v_add_u32_e32 v17, 0x1e00, v196
	v_lshl_add_u32 v56, v14, 2, v11
	v_mul_u32_u24_e32 v14, 0x1800, v7
	v_and_b32_e32 v7, 0xfc0, v15
	v_lshrrev_b32_e32 v60, 10, v17
	v_add_u32_e32 v17, 0x1a00, v196
	v_lshl_add_u32 v57, v7, 2, v11
	v_lshrrev_b32_e32 v7, 6, v15
	v_lshrrev_b32_e32 v62, 10, v17
	v_add_u32_e32 v17, 0x1600, v196
	v_lshrrev_b32_e32 v8, 6, v196
	v_mul_u32_u24_e32 v16, 0x1800, v7
	v_lshlrev_b32_e32 v7, 7, v196
	v_lshrrev_b32_e32 v63, 10, v17
	v_add_u32_e32 v17, 0x1200, v196
	v_lshlrev_b32_e32 v13, 13, v8
	v_mov_b32_e32 v3, 0
	v_mul_u32_u24_e32 v10, 0x1800, v8
	v_add_u32_e32 v58, 0, v7
	v_xor_b32_e32 v7, 0x10000, v7
	v_readlane_b32 s0, v249, 9
	v_lshrrev_b32_e32 v64, 10, v17
	v_add_u32_e32 v17, 0xe00, v196
	v_lshrrev_b32_e32 v68, 10, v9
	v_lshl_add_u32 v69, v8, 14, 0
	v_mul_hi_u32_u24_e32 v9, 0x300000, v8
	v_mul_u32_u24_e32 v8, 0x300000, v8
	v_lshlrev_b32_e32 v6, 2, v196
	v_add_u32_e32 v59, 0, v7
	v_mov_b32_e32 v7, v3
	v_readlane_b32 s2, v249, 11
	v_readlane_b32 s3, v249, 12
	v_readlane_b32 s4, v249, 13
	v_readlane_b32 s5, v249, 14
	s_mov_b32 s0, 0x34000
	v_lshrrev_b32_e32 v65, 10, v17
	v_add_u32_e32 v17, 0xa00, v196
	v_or_b32_e32 v8, v8, v2
	v_and_b32_e32 v1, 28, v6
	v_lshl_add_u64 v[4:5], s[76:77], 0, v[2:3]
	v_lshl_add_u64 v[6:7], s[2:3], 0, v[6:7]
	v_lshl_add_u32 v61, v196, 5, s0
	v_lshrrev_b32_e32 v66, 10, v17
	v_lshrrev_b32_e32 v67, 10, v15
	v_lshl_add_u64 v[8:9], s[4:5], 0, v[8:9]
	s_lshl_b32 s60, s94, 6
	s_lshl_b32 s33, s82, 6
	s_movk_i32 s65, 0x6000
	v_add_u32_e32 v70, v11, v13
	v_lshlrev_b32_e32 v2, 2, v10
	v_lshlrev_b32_e32 v10, 2, v12
	v_lshlrev_b32_e32 v12, 2, v14
	v_lshlrev_b32_e32 v14, 2, v16
	s_mov_b32 s66, s94
	v_readlane_b32 s1, v249, 10
	v_readlane_b32 s6, v249, 15
	v_readlane_b32 s7, v249, 16
	v_readlane_b32 s8, v249, 17
	v_readlane_b32 s9, v249, 18
	v_readlane_b32 s10, v249, 19
	v_readlane_b32 s11, v249, 20
	v_readlane_b32 s12, v249, 21
	v_readlane_b32 s13, v249, 22
	v_readlane_b32 s14, v249, 23
	v_readlane_b32 s15, v249, 24

.LBB0_184:
	s_or_b64 exec, exec, s[0:1]
	s_cmp_gt_i32 s91, 1
	s_mov_b32 s0, 0
	v_writelane_b32 v249, s0, 33
	s_cbranch_scc0 .LBB0_199
	s_cmpk_eq_i32 s82, 0x100
	s_cbranch_scc1 .Lsd0_begin
	v_lshrrev_b32_e32 v1, 20, v0
	v_lshrrev_b32_e32 v0, 10, v0
	v_or_b32_e32 v0, v0, v1
	s_movk_i32 s0, 0x3ff
	v_and_or_b32 v0, v0, s0, v196
	v_cmp_eq_u32_e32 vcc, 0, v0
	s_waitcnt lgkmcnt(0)
	s_barrier
	s_and_saveexec_b64 s[0:1], vcc
	s_cbranch_execz .LBB0_195
	buffer_wbl2 sc1
	s_waitcnt vmcnt(0)
	s_load_dwordx2 s[2:3], s[58:59], 0x58
	v_mov_b32_e32 v2, 0
	s_mov_b64 s[4:5], exec
	v_mbcnt_lo_u32_b32 v1, s4, 0
	v_mbcnt_hi_u32_b32 v1, s5, v1
	s_waitcnt lgkmcnt(0)
	global_load_dword v0, v2, s[2:3] offset:40
	v_cmp_eq_u32_e32 vcc, 0, v1
	s_and_saveexec_b64 s[6:7], vcc
	s_cbranch_execz .LBB0_188
	s_bcnt1_i32_b64 s4, s[4:5]
	v_mov_b32_e32 v3, s4
	global_atomic_add v3, v2, v3, s[2:3] offset:32 sc0

.LBB0_198:
	s_or_b64 exec, exec, s[0:1]
	s_branch .LBB0_199
.Lsd0_begin:
	s_waitcnt vmcnt(0) lgkmcnt(0)
	s_barrier
	s_getreg_b32 s0, hwreg(HW_REG_XCC_ID, 0, 4)
	s_and_b32 s0, s0, 15
	v_writelane_b32 v249, s0, 33
	s_and_saveexec_b64 s[0:1], s[92:93]
	s_cbranch_execz .Lsd0_end
	buffer_wbl2 sc1
	s_waitcnt vmcnt(0)
	s_add_u32 s4, s88, 0x8000
	s_addc_u32 s5, s89, 0
	s_mov_b32 s6, 0x5ada1e55
	v_mov_b32_e32 v0, 0
	s_mov_b32 s2, 0
.Lsd0_zpoll:
	global_load_dword v1, v0, s[4:5] sc1
	s_waitcnt vmcnt(0)
	v_cmp_eq_u32_e32 vcc, s6, v1
	s_cbranch_vccnz .Lsd0_zok
	s_sleep 1
	s_add_i32 s2, s2, 1
	s_cmp_lt_u32 s2, 0x40000
	s_cbranch_scc1 .Lsd0_zpoll
.Lsd0_zok:
	v_readlane_b32 s3, v249, 33
	s_lshl_b32 s3, s3, 8
	v_mov_b32_e32 v2, s3
	v_mov_b32_e32 v3, 1
	global_atomic_add v2, v3, s[88:89] offset:1024
	s_and_b32 s4, s94, 7
	s_lshl_b32 s4, 1, s4
	v_mov_b32_e32 v4, s4
	global_atomic_or v2, v4, s[88:89] offset:1152
	s_cmp_lt_u32 s94, 32
	s_cbranch_scc0 .Lsd0_nomod
	global_atomic_add v0, v3, s[88:89] offset:256
.Lsd0_nomod:
	s_waitcnt vmcnt(0)
	global_atomic_add v0, v3, s[88:89] offset:768
	s_mov_b32 s2, 0
.Lsd0_mpoll:
	global_load_dword v1, v0, s[88:89] offset:256 sc1
	s_waitcnt vmcnt(0)
	v_cmp_le_u32_e32 vcc, 32, v1
	s_cbranch_vccnz .Lsd0_mok
	s_sleep 2
	s_add_i32 s2, s2, 1
	s_cmp_lt_u32 s2, 0x40000
	s_cbranch_scc1 .Lsd0_mpoll

.Lsd0_end:
	s_or_b64 exec, exec, s[0:1]
	s_barrier
.LBB0_199:
	s_cmp_lt_i32 s90, 2
	s_cselect_b64 s[0:1], -1, 0
	s_cmp_gt_i32 s91, 1
	s_cselect_b64 s[2:3], -1, 0
	s_and_b64 s[0:1], s[0:1], s[2:3]
	s_andn2_b64 vcc, exec, s[0:1]
	s_cbranch_vccnz .LBB0_255
	s_lshl_b32 s0, s95, 8
	s_lshl_b32 s1, s78, 5
	s_add_i32 s8, s0, s1
	s_cmp_gt_i32 s8, 0xffff
	s_cbranch_scc1 .LBB0_205
	v_mbcnt_lo_u32_b32 v1, -1, 0
	v_mbcnt_hi_u32_b32 v1, -1, v1
	v_and_b32_e32 v5, 64, v1
	v_add_u32_e32 v5, 64, v5
	v_xor_b32_e32 v7, 1, v1
	v_cmp_lt_i32_e32 vcc, v7, v5
	v_readlane_b32 s12, v249, 9
	v_readlane_b32 s13, v249, 10
	v_cndmask_b32_e32 v7, v1, v7, vcc
	v_lshlrev_b32_e32 v108, 2, v7
	v_xor_b32_e32 v7, 2, v1
	v_cmp_lt_i32_e32 vcc, v7, v5
	s_ashr_i32 s9, s8, 31
	s_mov_b64 s[4:5], s[12:13]
	v_cndmask_b32_e32 v7, v1, v7, vcc
	v_lshlrev_b32_e32 v109, 2, v7
	v_xor_b32_e32 v7, 4, v1
	v_cmp_lt_i32_e32 vcc, v7, v5
	s_lshl_b32 s10, s82, 8
	s_lshl_b64 s[0:1], s[8:9], 12
	v_cndmask_b32_e32 v7, v1, v7, vcc
	v_lshlrev_b32_e32 v110, 2, v7
	v_xor_b32_e32 v7, 8, v1
	v_cmp_lt_i32_e32 vcc, v7, v5
	s_add_u32 s0, s4, s0
	v_mov_b32_e32 v3, 0
	v_cndmask_b32_e32 v7, v1, v7, vcc
	v_lshlrev_b32_e32 v2, 4, v199
	v_readlane_b32 s20, v249, 17
	v_readlane_b32 s21, v249, 18
	v_lshlrev_b32_e32 v111, 2, v7
	v_xor_b32_e32 v7, 16, v1
	s_addc_u32 s1, s5, s1
	s_mov_b64 s[12:13], s[20:21]
	v_cmp_lt_i32_e32 vcc, v7, v5
	v_lshl_add_u64 v[10:11], s[0:1], 0, v[2:3]
	s_mov_b64 s[0:1], 0x3c00
	s_ashr_i32 s11, s10, 31
	v_lshl_add_u64 v[80:81], s[12:13], 0, v[2:3]
	v_cndmask_b32_e32 v7, v1, v7, vcc
	v_lshl_add_u64 v[82:83], v[10:11], 0, s[0:1]
	s_lshl_b64 s[12:13], s[10:11], 12
	s_lshl_b64 s[0:1], s[8:9], 11
	v_lshlrev_b32_e32 v112, 2, v7
	v_xor_b32_e32 v7, 32, v1
	s_add_u32 s0, s88, s0
	v_lshlrev_b32_e32 v0, 2, v199
	v_cmp_lt_i32_e32 vcc, v7, v5
	v_lshlrev_b32_e32 v2, 3, v199
	s_addc_u32 s1, s89, s1
	v_readlane_b32 s14, v249, 11
	v_readlane_b32 s15, v249, 12
	v_readlane_b32 s16, v249, 13
	v_readlane_b32 s17, v249, 14
	v_readlane_b32 s18, v249, 15
	v_readlane_b32 s19, v249, 16
	v_or_b32_e32 v4, 0x100, v0
	v_or_b32_e32 v6, 0x200, v0
	v_or_b32_e32 v8, 0x300, v0
	v_cndmask_b32_e32 v1, v1, v7, vcc
	v_lshl_add_u64 v[2:3], s[0:1], 0, v[2:3]
	s_mov_b64 s[0:1], 0x4001e00
	v_lshlrev_b32_e32 v113, 2, v1
	v_lshl_add_u64 v[84:85], v[2:3], 0, s[0:1]
	s_lshl_b64 s[14:15], s[10:11], 11
	v_lshlrev_b32_e32 v114, 2, v0
	v_lshlrev_b32_e32 v115, 2, v4
	v_lshlrev_b32_e32 v116, 2, v6
	v_lshlrev_b32_e32 v117, 2, v8
	s_movk_i32 s9, 0xf000
	v_mov_b32_e32 v118, 0x358637bd
	s_mov_b32 s11, 0xf800000
	v_mov_b32_e32 v119, 0x260
	s_mov_b64 s[16:17], 0x4000
	s_mov_b64 s[18:19], 0x2000
	v_readlane_b32 s22, v249, 19
	v_readlane_b32 s23, v249, 20
	v_readlane_b32 s24, v249, 21
	v_readlane_b32 s25, v249, 22
	v_readlane_b32 s26, v249, 23
	v_readlane_b32 s27, v249, 24

.LBB0_205:
	s_cmp_gt_i32 s91, 2
	s_cbranch_scc0 .LBB0_255
	s_waitcnt vmcnt(0)
	s_waitcnt lgkmcnt(0)
	s_barrier
	s_and_saveexec_b64 s[0:1], s[92:93]
	s_cbranch_execz .LBB0_254
	s_add_i32 s2, 0, 0x20088
	v_mov_b32_e32 v0, s2
	ds_read_b32 v3, v0
	s_waitcnt lgkmcnt(0)
	v_readfirstlane_b32 s3, v3
	s_cmp_eq_u32 s3, 1
	s_cbranch_scc1 .Lsd1_fast
	s_cmp_eq_u32 s3, 2
	s_cbranch_scc1 .Lsd1_slow
	s_mov_b32 s3, 2
	s_cmpk_lg_i32 s82, 0x100
	s_cbranch_scc1 .Lsd1_set
	v_mov_b32_e32 v4, 0
	s_mov_b32 s4, 0
.Lsd1_ppoll:
	global_load_dword v5, v4, s[88:89] offset:768 sc1
	s_waitcnt vmcnt(0)
	v_cmp_le_u32_e32 vcc, 0x100, v5
	s_cbranch_vccnz .Lsd1_pok
	s_sleep 1
	s_add_i32 s4, s4, 1
	s_cmp_lt_u32 s4, 0x40000
	s_cbranch_scc1 .Lsd1_ppoll
	s_branch .Lsd1_set
.Lsd1_pok:
	s_mov_b32 exec_lo, 0xffff
	s_mov_b32 exec_hi, 0
	v_mbcnt_lo_u32_b32 v4, -1, 0
	v_lshlrev_b32_e32 v4, 8, v4
	global_load_dword v5, v4, s[88:89] offset:1024 sc1
	global_load_dword v6, v4, s[88:89] offset:1152 sc1
	s_waitcnt vmcnt(0)
	v_add_u32_e32 v7, -1, v6
	v_and_b32_e32 v7, v7, v6
	v_cmp_eq_u32_e32 vcc, 0, v7
	v_cmp_eq_u32_e64 s[4:5], 32, v5
	v_cmp_ne_u32_e64 s[6:7], 0, v6
	v_cmp_eq_u32_e64 s[8:9], 0, v5
	s_and_b64 s[4:5], s[4:5], s[6:7]
	s_andn2_b64 s[8:9], s[8:9], s[6:7]
	s_or_b64 s[4:5], s[4:5], s[8:9]
	s_and_b64 s[4:5], s[4:5], vcc
	s_cmp_eq_u64 s[4:5], exec
	s_cselect_b32 s3, 1, 2
	s_mov_b64 exec, 1
	s_add_i32 s4, s82, -1
	s_cmp_lg_u32 s94, s4
	s_cbranch_scc1 .Lsd1_set
	s_add_u32 s4, s88, 0x8000
	s_addc_u32 s5, s89, 0
	v_mov_b32_e32 v4, 0
	v_mov_b32_e32 v5, 0
	global_atomic_swap v4, v5, s[4:5]
.Lsd1_set:
	v_mov_b32_e32 v4, s3
	ds_write_b32 v0, v4
	s_cmp_eq_u32 s3, 1
	s_cbranch_scc0 .Lsd1_slow
.Lsd1_fast:
	v_readlane_b32 s2, v249, 33
	s_lshl_b32 s2, s2, 8
	s_add_u32 s2, s88, s2
	s_addc_u32 s3, s89, 0
	v_mov_b32_e32 v1, 0x1000
	v_mov_b32_e32 v3, 1
	global_atomic_add v3, v1, v3, s[2:3] offset:1024 sc0
	s_waitcnt vmcnt(0)
	v_readfirstlane_b32 s4, v3
	v_mov_b32_e32 v0, 0x2000
	s_lshr_b32 s5, s4, 5
	s_add_i32 s4, s4, 1
	s_and_b32 s4, s4, 31
	s_cmp_eq_u32 s4, 0
	s_cbranch_scc1 .Lsd1_last
	s_mov_b32 s6, 0
.Lsd1_poll:
	global_load_dword v2, v0, s[2:3] offset:1024 sc1
	s_waitcnt vmcnt(0)
	v_cmp_ne_u32_e32 vcc, s5, v2
	s_cbranch_vccnz .Lsd1_acq
	s_sleep 1
	s_add_i32 s6, s6, 1
	s_cmp_lt_u32 s6, 0x40000
	s_cbranch_scc1 .Lsd1_poll
	s_branch .Lsd1_acq
.Lsd1_last:
	v_mov_b32_e32 v1, 1
	global_atomic_add v0, v1, s[2:3] offset:1024
	s_waitcnt vmcnt(0)
.Lsd1_acq:
	buffer_inv sc1
	s_waitcnt vmcnt(0)
	s_branch .LBB0_254
.Lsd1_slow:
	s_add_i32 s2, 0, 0x20080
	v_mov_b32_e32 v0, s2
	s_waitcnt vmcnt(0) expcnt(0) lgkmcnt(0)
	ds_read_b32 v2, v0
	s_add_i32 s2, 0, 0x20084
	v_mov_b32_e32 v0, s2
	ds_read_b32 v0, v0
	s_waitcnt lgkmcnt(1)
	v_cmp_ne_u32_e32 vcc, 0, v2
	s_cbranch_vccnz .LBB0_222
	v_readlane_b32 s2, v249, 8
	s_mul_i32 s16, s83, s2
	s_add_u32 s2, s88, 0x1000
	s_addc_u32 s3, s89, 0
	s_add_u32 s4, s88, 0x1100
	s_addc_u32 s5, s89, 0
	s_add_u32 s6, s88, 0x1200
	s_addc_u32 s7, s89, 0
	s_add_u32 s8, s88, 0x1300
	s_mul_i32 s16, s16, s82
	s_addc_u32 s9, s89, 0
	s_mov_b32 s17, 1
	v_mov_b32_e32 v16, 0
	s_branch .LBB0_210

.LBB0_355:
	s_waitcnt vmcnt(0)
	s_waitcnt vmcnt(0) lgkmcnt(0)
	s_barrier
	s_and_saveexec_b64 s[0:1], s[92:93]
	s_cbranch_execz .LBB0_403
	s_add_i32 s2, 0, 0x20088
	v_mov_b32_e32 v0, s2
	ds_read_b32 v3, v0
	s_waitcnt lgkmcnt(0)
	v_readfirstlane_b32 s3, v3
	s_cmp_eq_u32 s3, 1
	s_cbranch_scc0 .Lsd2_slow

.Lsd2_slow:
	s_add_i32 s2, 0, 0x20080
	v_mov_b32_e32 v0, s2
	s_waitcnt vmcnt(0) expcnt(0) lgkmcnt(0)
	ds_read_b32 v2, v0
	s_add_i32 s2, 0, 0x20084
	v_mov_b32_e32 v0, s2
	ds_read_b32 v0, v0
	s_waitcnt lgkmcnt(1)
	v_cmp_ne_u32_e32 vcc, 0, v2
	s_cbranch_vccnz .LBB0_371
	v_readlane_b32 s2, v249, 8
	s_mul_i32 s18, s83, s2
	s_add_u32 s2, s88, 0x1000
	s_addc_u32 s3, s89, 0
	s_add_u32 s4, s88, 0x1100
	s_addc_u32 s5, s89, 0
	s_add_u32 s6, s88, 0x1200
	s_addc_u32 s7, s89, 0
	s_add_u32 s8, s88, 0x1300
	s_mul_i32 s18, s18, s82
	s_addc_u32 s9, s89, 0
	s_mov_b32 s19, 1
	v_mov_b32_e32 v16, 0
	s_branch .LBB0_359

.LBB0_493:
	s_cmp_lt_i32 s91, 5
	s_cbranch_scc1 .LBB0_543
	s_waitcnt vmcnt(0)
	s_waitcnt vmcnt(0) lgkmcnt(0)
	s_barrier
	s_and_saveexec_b64 s[0:1], s[92:93]
	s_cbranch_execz .LBB0_542
	s_add_i32 s2, 0, 0x20088
	v_mov_b32_e32 v0, s2
	ds_read_b32 v3, v0
	s_waitcnt lgkmcnt(0)
	v_readfirstlane_b32 s3, v3
	s_cmp_eq_u32 s3, 1
	s_cbranch_scc0 .Lsd3_slow

.LBB0_662:
	v_readlane_b32 s84, v249, 51
	v_readlane_b32 s91, v249, 58
	v_readlane_b32 s92, v249, 49
	v_readlane_b32 s76, v249, 40
	v_readlane_b32 s85, v249, 52
	v_readlane_b32 s86, v249, 53
	v_readlane_b32 s87, v249, 54
	v_readlane_b32 s88, v249, 55
	v_readlane_b32 s89, v249, 56
	v_readlane_b32 s90, v249, 57
	s_cmp_gt_i32 s91, 5
	v_readlane_b32 s93, v249, 50
	v_readlane_b32 s94, v249, 48
	v_readlane_b32 s77, v249, 41
	s_waitcnt vmcnt(0) lgkmcnt(0)
	s_barrier
	s_cbranch_scc0 .LBB0_712
	s_waitcnt vmcnt(0)
	s_barrier
	s_and_saveexec_b64 s[0:1], s[92:93]
	s_cbranch_execz .LBB0_711
	s_add_i32 s2, 0, 0x20088
	v_mov_b32_e32 v0, s2
	ds_read_b32 v3, v0
	s_waitcnt lgkmcnt(0)
	v_readfirstlane_b32 s3, v3
	s_cmp_eq_u32 s3, 1
	s_cbranch_scc0 .Lsd4_slow

.LBB0_821:
	s_cmp_lt_i32 s91, 8
	s_cbranch_scc1 .LBB0_871
	s_waitcnt vmcnt(0)
	s_waitcnt vmcnt(0) lgkmcnt(0)
	s_barrier
	s_and_saveexec_b64 s[0:1], s[92:93]
	s_cbranch_execz .LBB0_870
	s_add_i32 s2, 0, 0x20088
	v_mov_b32_e32 v0, s2
	ds_read_b32 v3, v0
	s_waitcnt lgkmcnt(0)
	v_readfirstlane_b32 s3, v3
	s_cmp_eq_u32 s3, 1
	s_cbranch_scc0 .Lsd5_slow

.LBB0_888:
	s_cmp_lt_i32 s91, 9
	s_cbranch_scc1 .LBB0_938
	s_waitcnt vmcnt(0)
	s_waitcnt vmcnt(0)
	s_barrier
	s_and_saveexec_b64 s[0:1], s[92:93]
	s_cbranch_execz .LBB0_937
	s_add_i32 s2, 0, 0x20088
	v_mov_b32_e32 v0, s2
	ds_read_b32 v3, v0
	s_waitcnt lgkmcnt(0)
	v_readfirstlane_b32 s3, v3
	s_cmp_eq_u32 s3, 1
	s_cbranch_scc0 .Lsd7_slow
